# in-proj GEMM: hand-written whole-tile epilogue for the sigmoid-gate tiles (bias loaded once, in-place fma/exp/add/rcp, stores not waited)
# speedup vs baseline: 1.0270x; 1.0034x over previous
.LBB0_168:
	s_cmp_gt_u32 s6, 14
	s_cbranch_scc1 .Lp2_sig
	s_lshl_b32 s65, s4, 8
	s_cmp_gt_i32 s6, 3
	s_cselect_b64 s[94:95], -1, 0
	v_readlane_b32 s66, v250, 46
	v_add_u32_e32 v148, s65, v139
	s_mov_b64 s[4:5], -1
	s_and_b64 vcc, exec, s[94:95]
	v_readlane_b32 s67, v250, 47
	s_cbranch_vccz .LBB0_196
	s_cmp_gt_u32 s6, 11
	s_cbranch_scc0 .LBB0_191
	s_cmp_gt_u32 s6, 14
	s_cbranch_scc0 .LBB0_174
	v_cmp_gt_i32_e32 vcc, s80, v148
	s_and_saveexec_b64 s[4:5], vcc
	s_cbranch_execz .LBB0_173
	s_cmp_gt_u32 s6, 18
	s_cselect_b64 s[12:13], -1, 0
	s_and_b64 s[52:53], s[12:13], exec
	s_cselect_b32 s3, 0xffffffed, -15
	s_add_i32 s3, s3, s6
	s_and_b64 s[52:53], s[12:13], exec
	v_readlane_b32 s36, v250, 22
	v_lshl_or_b32 v136, s3, 8, v138
	s_cselect_b32 s3, 0x1000, 0
	v_readlane_b32 s38, v250, 24
	v_readlane_b32 s39, v250, 25
	s_add_u32 s52, s38, s3
	s_addc_u32 s53, s39, 0
	v_lshl_add_u64 v[174:175], v[136:137], 2, s[52:53]
	global_load_dwordx4 v[162:165], v[174:175], off
	global_load_dwordx4 v[166:169], v[174:175], off offset:16
	global_load_dwordx4 v[170:173], v[174:175], off offset:512
	s_nop 0
	global_load_dwordx4 v[174:177], v[174:175], off offset:528
	v_ashrrev_i32_e32 v149, 31, v148
	v_lshlrev_b64 v[178:179], 11, v[148:149]
	v_readlane_b32 s44, v250, 30
	v_readlane_b32 s45, v250, 31
	v_readlane_b32 s44, v250, 52
	v_readlane_b32 s45, v250, 53
	s_and_b64 s[12:13], s[12:13], exec
	v_readlane_b32 s42, v250, 28
	v_readlane_b32 s43, v250, 29
	s_cselect_b32 s13, s45, s31
	s_cselect_b32 s12, s44, s30
	v_readlane_b32 s42, v250, 50
	v_readlane_b32 s38, v250, 38
	v_lshl_add_u64 v[178:179], s[12:13], 0, v[178:179]
	v_readlane_b32 s43, v250, 51
	v_readlane_b32 s39, v250, 39
	v_readlane_b32 s37, v250, 23
	v_readlane_b32 s40, v250, 26
	v_readlane_b32 s41, v250, 27
	v_readlane_b32 s46, v250, 32
	v_readlane_b32 s47, v250, 33
	v_readlane_b32 s48, v250, 34
	v_readlane_b32 s49, v250, 35
	v_readlane_b32 s50, v250, 36
	v_readlane_b32 s51, v250, 37
	s_waitcnt vmcnt(0)
	v_add_f32_e32 v149, v124, v162
	v_add_f32_e32 v161, v120, v166
	v_add_f32_e32 v162, v116, v170
	v_add_f32_e32 v166, v112, v174
	v_add_f32_e32 v163, v125, v163
	v_add_f32_e32 v164, v126, v164
	v_add_f32_e32 v165, v127, v165
	v_add_f32_e32 v169, v123, v169
	v_add_f32_e32 v167, v121, v167
	v_add_f32_e32 v170, v117, v171
	v_add_f32_e32 v171, v113, v175
	v_add_f32_e32 v168, v122, v168
	v_add_f32_e32 v173, v119, v173
	v_add_f32_e32 v175, v115, v177
	v_mul_f32_e32 v162, 0xbfb8aa3b, v162
	v_mul_f32_e32 v166, 0xbfb8aa3b, v166
	v_mul_f32_e32 v163, 0xbfb8aa3b, v163
	v_mul_f32_e32 v164, 0xbfb8aa3b, v164
	v_mul_f32_e32 v165, 0xbfb8aa3b, v165
	v_mul_f32_e32 v169, 0xbfb8aa3b, v169
	v_add_f32_e32 v172, v118, v172
	v_add_f32_e32 v174, v114, v176
	v_mul_f32_e32 v149, 0xbfb8aa3b, v149
	v_mul_f32_e32 v161, 0xbfb8aa3b, v161
	v_mul_f32_e32 v167, 0xbfb8aa3b, v167
	v_mul_f32_e32 v168, 0xbfb8aa3b, v168
	v_mul_f32_e32 v173, 0xbfb8aa3b, v173
	v_mul_f32_e32 v175, 0xbfb8aa3b, v175
	v_exp_f32_e32 v162, v162
	v_exp_f32_e32 v166, v166
	v_exp_f32_e32 v163, v163
	v_exp_f32_e32 v164, v164
	v_exp_f32_e32 v165, v165
	v_exp_f32_e32 v169, v169
	v_mul_f32_e32 v170, 0xbfb8aa3b, v170
	v_mul_f32_e32 v171, 0xbfb8aa3b, v171
	v_mul_f32_e32 v172, 0xbfb8aa3b, v172
	v_mul_f32_e32 v174, 0xbfb8aa3b, v174
	v_exp_f32_e32 v149, v149
	v_exp_f32_e32 v161, v161
	v_exp_f32_e32 v167, v167
	v_exp_f32_e32 v168, v168
	v_exp_f32_e32 v173, v173
	v_exp_f32_e32 v175, v175
	v_exp_f32_e32 v170, v170
	v_exp_f32_e32 v171, v171
	v_exp_f32_e32 v172, v172
	v_exp_f32_e32 v174, v174
	v_add_f32_e32 v162, 1.0, v162
	v_add_f32_e32 v166, 1.0, v166
	v_add_f32_e32 v163, 1.0, v163
	v_add_f32_e32 v164, 1.0, v164
	v_add_f32_e32 v165, 1.0, v165
	v_add_f32_e32 v169, 1.0, v169
	v_add_f32_e32 v149, 1.0, v149
	v_add_f32_e32 v161, 1.0, v161
	v_add_f32_e32 v167, 1.0, v167
	v_add_f32_e32 v168, 1.0, v168
	v_add_f32_e32 v173, 1.0, v173
	v_rcp_f32_e32 v176, v162
	v_rcp_f32_e32 v177, v166
	v_rcp_f32_e32 v162, v163
	v_rcp_f32_e32 v163, v164
	v_rcp_f32_e32 v164, v165
	v_rcp_f32_e32 v165, v169
	v_add_f32_e32 v166, 1.0, v175
	v_add_f32_e32 v170, 1.0, v170
	v_add_f32_e32 v171, 1.0, v171
	v_add_f32_e32 v172, 1.0, v172
	v_add_f32_e32 v174, 1.0, v174
	v_rcp_f32_e32 v149, v149
	v_rcp_f32_e32 v161, v161
	v_rcp_f32_e32 v180, v167
	v_rcp_f32_e32 v168, v168
	v_rcp_f32_e32 v169, v173
	v_rcp_f32_e32 v173, v166
	v_lshl_add_u64 v[166:167], v[136:137], 1, v[178:179]
	v_cvt_pk_bf16_f32 v162, v149, v162
	v_cvt_pk_bf16_f32 v163, v163, v164
	v_cvt_pk_bf16_f32 v164, v161, v180
	v_cvt_pk_bf16_f32 v165, v168, v165
	v_rcp_f32_e32 v170, v170
	v_rcp_f32_e32 v171, v171
	v_rcp_f32_e32 v172, v172
	v_rcp_f32_e32 v174, v174
	global_store_dwordx4 v[166:167], v[162:165], off
	s_nop 1
	v_cvt_pk_bf16_f32 v162, v176, v170
	v_cvt_pk_bf16_f32 v163, v172, v169
	v_cvt_pk_bf16_f32 v164, v177, v171
	v_cvt_pk_bf16_f32 v165, v174, v173
	global_store_dwordx4 v[166:167], v[162:165], off offset:256

.Lp2_sig:
	s_cmp_gt_u32 s4, 63
	s_cbranch_scc1 .LBB0_396
	v_readlane_b32 s36, v250, 24
	v_readlane_b32 s37, v250, 25
	v_readlane_b32 s40, v250, 52
	v_readlane_b32 s41, v250, 53
	s_cmp_gt_u32 s6, 18
	s_cselect_b32 s3, 0xffffffed, -15
	s_cselect_b32 s46, 0x1000, 0
	s_cselect_b32 s40, s40, s30
	s_cselect_b32 s41, s41, s31
	s_add_i32 s3, s3, s6
	s_add_u32 s36, s36, s46
	s_addc_u32 s37, s37, 0
	v_lshl_or_b32 v136, s3, 8, v138
	v_lshl_add_u64 v[178:179], v[136:137], 2, s[36:37]
	global_load_dwordx4 v[162:165], v[178:179], off
	global_load_dwordx4 v[166:169], v[178:179], off offset:16
	global_load_dwordx4 v[170:173], v[178:179], off offset:512
	global_load_dwordx4 v[174:177], v[178:179], off offset:528
	s_lshl_b32 s65, s4, 8
	v_add_u32_e32 v148, s65, v139
	v_ashrrev_i32_e32 v149, 31, v148
	v_lshlrev_b64 v[148:149], 11, v[148:149]
	v_lshl_add_u64 v[148:149], s[40:41], 0, v[148:149]
	v_lshl_add_u64 v[148:149], v[136:137], 1, v[148:149]
	s_mov_b32 s98, 0x8000
	s_mov_b32 s99, 0
	s_mov_b32 s100, 0x28000
	s_mov_b32 s101, 0
	s_mov_b32 s47, 0xbfb8aa3b
	s_waitcnt vmcnt(0)
	v_mul_f32_e32 v162, s47, v162
	v_mul_f32_e32 v163, s47, v163
	v_mul_f32_e32 v164, s47, v164
	v_mul_f32_e32 v165, s47, v165
	v_mul_f32_e32 v166, s47, v166
	v_mul_f32_e32 v167, s47, v167
	v_mul_f32_e32 v168, s47, v168
	v_mul_f32_e32 v169, s47, v169
	v_mul_f32_e32 v170, s47, v170
	v_mul_f32_e32 v171, s47, v171
	v_mul_f32_e32 v172, s47, v172
	v_mul_f32_e32 v173, s47, v173
	v_mul_f32_e32 v174, s47, v174
	v_mul_f32_e32 v175, s47, v175
	v_mul_f32_e32 v176, s47, v176
	v_mul_f32_e32 v177, s47, v177
	v_fma_f32 v124, v124, s47, v162
	v_fma_f32 v125, v125, s47, v163
	v_fma_f32 v126, v126, s47, v164
	v_fma_f32 v127, v127, s47, v165
	v_fma_f32 v120, v120, s47, v166
	v_fma_f32 v121, v121, s47, v167
	v_fma_f32 v122, v122, s47, v168
	v_fma_f32 v123, v123, s47, v169
	v_fma_f32 v116, v116, s47, v170
	v_fma_f32 v117, v117, s47, v171
	v_fma_f32 v118, v118, s47, v172
	v_fma_f32 v119, v119, s47, v173
	v_fma_f32 v112, v112, s47, v174
	v_fma_f32 v113, v113, s47, v175
	v_fma_f32 v114, v114, s47, v176
	v_fma_f32 v115, v115, s47, v177
	v_exp_f32_e32 v124, v124
	v_exp_f32_e32 v125, v125
	v_exp_f32_e32 v126, v126
	v_exp_f32_e32 v127, v127
	v_exp_f32_e32 v120, v120
	v_exp_f32_e32 v121, v121
	v_exp_f32_e32 v122, v122
	v_exp_f32_e32 v123, v123
	v_exp_f32_e32 v116, v116
	v_exp_f32_e32 v117, v117
	v_exp_f32_e32 v118, v118
	v_exp_f32_e32 v119, v119
	v_exp_f32_e32 v112, v112
	v_exp_f32_e32 v113, v113
	v_exp_f32_e32 v114, v114
	v_exp_f32_e32 v115, v115
	v_add_f32_e32 v124, 1.0, v124
	v_add_f32_e32 v125, 1.0, v125
	v_add_f32_e32 v126, 1.0, v126
	v_add_f32_e32 v127, 1.0, v127
	v_add_f32_e32 v120, 1.0, v120
	v_add_f32_e32 v121, 1.0, v121
	v_add_f32_e32 v122, 1.0, v122
	v_add_f32_e32 v123, 1.0, v123
	v_add_f32_e32 v116, 1.0, v116
	v_add_f32_e32 v117, 1.0, v117
	v_add_f32_e32 v118, 1.0, v118
	v_add_f32_e32 v119, 1.0, v119
	v_add_f32_e32 v112, 1.0, v112
	v_add_f32_e32 v113, 1.0, v113
	v_add_f32_e32 v114, 1.0, v114
	v_add_f32_e32 v115, 1.0, v115
	v_rcp_f32_e32 v124, v124
	v_rcp_f32_e32 v125, v125
	v_rcp_f32_e32 v126, v126
	v_rcp_f32_e32 v127, v127
	v_rcp_f32_e32 v120, v120
	v_rcp_f32_e32 v121, v121
	v_rcp_f32_e32 v122, v122
	v_rcp_f32_e32 v123, v123
	v_rcp_f32_e32 v116, v116
	v_rcp_f32_e32 v117, v117
	v_rcp_f32_e32 v118, v118
	v_rcp_f32_e32 v119, v119
	v_rcp_f32_e32 v112, v112
	v_rcp_f32_e32 v113, v113
	v_rcp_f32_e32 v114, v114
	v_rcp_f32_e32 v115, v115
	v_cvt_pk_bf16_f32 v124, v124, v125
	v_cvt_pk_bf16_f32 v125, v126, v127
	v_cvt_pk_bf16_f32 v126, v120, v121
	v_cvt_pk_bf16_f32 v127, v122, v123
	global_store_dwordx4 v[148:149], v[124:127], off
	v_cvt_pk_bf16_f32 v116, v116, v117
	v_cvt_pk_bf16_f32 v117, v118, v119
	v_cvt_pk_bf16_f32 v118, v112, v113
	v_cvt_pk_bf16_f32 v119, v114, v115
	global_store_dwordx4 v[148:149], v[116:119], off offset:256
	v_lshl_add_u64 v[148:149], v[148:149], 0, s[98:99]
	v_fma_f32 v108, v108, s47, v162
	v_fma_f32 v109, v109, s47, v163
	v_fma_f32 v110, v110, s47, v164
	v_fma_f32 v111, v111, s47, v165
	v_fma_f32 v104, v104, s47, v166
	v_fma_f32 v105, v105, s47, v167
	v_fma_f32 v106, v106, s47, v168
	v_fma_f32 v107, v107, s47, v169
	v_fma_f32 v100, v100, s47, v170
	v_fma_f32 v101, v101, s47, v171
	v_fma_f32 v102, v102, s47, v172
	v_fma_f32 v103, v103, s47, v173
	v_fma_f32 v96, v96, s47, v174
	v_fma_f32 v97, v97, s47, v175
	v_fma_f32 v98, v98, s47, v176
	v_fma_f32 v99, v99, s47, v177
	v_exp_f32_e32 v108, v108
	v_exp_f32_e32 v109, v109
	v_exp_f32_e32 v110, v110
	v_exp_f32_e32 v111, v111
	v_exp_f32_e32 v104, v104
	v_exp_f32_e32 v105, v105
	v_exp_f32_e32 v106, v106
	v_exp_f32_e32 v107, v107
	v_exp_f32_e32 v100, v100
	v_exp_f32_e32 v101, v101
	v_exp_f32_e32 v102, v102
	v_exp_f32_e32 v103, v103
	v_exp_f32_e32 v96, v96
	v_exp_f32_e32 v97, v97
	v_exp_f32_e32 v98, v98
	v_exp_f32_e32 v99, v99
	v_add_f32_e32 v108, 1.0, v108
	v_add_f32_e32 v109, 1.0, v109
	v_add_f32_e32 v110, 1.0, v110
	v_add_f32_e32 v111, 1.0, v111
	v_add_f32_e32 v104, 1.0, v104
	v_add_f32_e32 v105, 1.0, v105
	v_add_f32_e32 v106, 1.0, v106
	v_add_f32_e32 v107, 1.0, v107
	v_add_f32_e32 v100, 1.0, v100
	v_add_f32_e32 v101, 1.0, v101
	v_add_f32_e32 v102, 1.0, v102
	v_add_f32_e32 v103, 1.0, v103
	v_add_f32_e32 v96, 1.0, v96
	v_add_f32_e32 v97, 1.0, v97
	v_add_f32_e32 v98, 1.0, v98
	v_add_f32_e32 v99, 1.0, v99
	v_rcp_f32_e32 v108, v108
	v_rcp_f32_e32 v109, v109
	v_rcp_f32_e32 v110, v110
	v_rcp_f32_e32 v111, v111
	v_rcp_f32_e32 v104, v104
	v_rcp_f32_e32 v105, v105
	v_rcp_f32_e32 v106, v106
	v_rcp_f32_e32 v107, v107
	v_rcp_f32_e32 v100, v100
	v_rcp_f32_e32 v101, v101
	v_rcp_f32_e32 v102, v102
	v_rcp_f32_e32 v103, v103
	v_rcp_f32_e32 v96, v96
	v_rcp_f32_e32 v97, v97
	v_rcp_f32_e32 v98, v98
	v_rcp_f32_e32 v99, v99
	v_cvt_pk_bf16_f32 v108, v108, v109
	v_cvt_pk_bf16_f32 v109, v110, v111
	v_cvt_pk_bf16_f32 v110, v104, v105
	v_cvt_pk_bf16_f32 v111, v106, v107
	global_store_dwordx4 v[148:149], v[108:111], off
	v_cvt_pk_bf16_f32 v100, v100, v101
	v_cvt_pk_bf16_f32 v101, v102, v103
	v_cvt_pk_bf16_f32 v102, v96, v97
	v_cvt_pk_bf16_f32 v103, v98, v99
	global_store_dwordx4 v[148:149], v[100:103], off offset:256
	v_lshl_add_u64 v[148:149], v[148:149], 0, s[98:99]
	v_fma_f32 v92, v92, s47, v162
	v_fma_f32 v93, v93, s47, v163
	v_fma_f32 v94, v94, s47, v164
	v_fma_f32 v95, v95, s47, v165
	v_fma_f32 v88, v88, s47, v166
	v_fma_f32 v89, v89, s47, v167
	v_fma_f32 v90, v90, s47, v168
	v_fma_f32 v91, v91, s47, v169
	v_fma_f32 v84, v84, s47, v170
	v_fma_f32 v85, v85, s47, v171
	v_fma_f32 v86, v86, s47, v172
	v_fma_f32 v87, v87, s47, v173
	v_fma_f32 v80, v80, s47, v174
	v_fma_f32 v81, v81, s47, v175
	v_fma_f32 v82, v82, s47, v176
	v_fma_f32 v83, v83, s47, v177
	v_exp_f32_e32 v92, v92
	v_exp_f32_e32 v93, v93
	v_exp_f32_e32 v94, v94
	v_exp_f32_e32 v95, v95
	v_exp_f32_e32 v88, v88
	v_exp_f32_e32 v89, v89
	v_exp_f32_e32 v90, v90
	v_exp_f32_e32 v91, v91
	v_exp_f32_e32 v84, v84
	v_exp_f32_e32 v85, v85
	v_exp_f32_e32 v86, v86
	v_exp_f32_e32 v87, v87
	v_exp_f32_e32 v80, v80
	v_exp_f32_e32 v81, v81
	v_exp_f32_e32 v82, v82
	v_exp_f32_e32 v83, v83
	v_add_f32_e32 v92, 1.0, v92
	v_add_f32_e32 v93, 1.0, v93
	v_add_f32_e32 v94, 1.0, v94
	v_add_f32_e32 v95, 1.0, v95
	v_add_f32_e32 v88, 1.0, v88
	v_add_f32_e32 v89, 1.0, v89
	v_add_f32_e32 v90, 1.0, v90
	v_add_f32_e32 v91, 1.0, v91
	v_add_f32_e32 v84, 1.0, v84
	v_add_f32_e32 v85, 1.0, v85
	v_add_f32_e32 v86, 1.0, v86
	v_add_f32_e32 v87, 1.0, v87
	v_add_f32_e32 v80, 1.0, v80
	v_add_f32_e32 v81, 1.0, v81
	v_add_f32_e32 v82, 1.0, v82
	v_add_f32_e32 v83, 1.0, v83
	v_rcp_f32_e32 v92, v92
	v_rcp_f32_e32 v93, v93
	v_rcp_f32_e32 v94, v94
	v_rcp_f32_e32 v95, v95
	v_rcp_f32_e32 v88, v88
	v_rcp_f32_e32 v89, v89
	v_rcp_f32_e32 v90, v90
	v_rcp_f32_e32 v91, v91
	v_rcp_f32_e32 v84, v84
	v_rcp_f32_e32 v85, v85
	v_rcp_f32_e32 v86, v86
	v_rcp_f32_e32 v87, v87
	v_rcp_f32_e32 v80, v80
	v_rcp_f32_e32 v81, v81
	v_rcp_f32_e32 v82, v82
	v_rcp_f32_e32 v83, v83
	v_cvt_pk_bf16_f32 v92, v92, v93
	v_cvt_pk_bf16_f32 v93, v94, v95
	v_cvt_pk_bf16_f32 v94, v88, v89
	v_cvt_pk_bf16_f32 v95, v90, v91
	global_store_dwordx4 v[148:149], v[92:95], off
	v_cvt_pk_bf16_f32 v84, v84, v85
	v_cvt_pk_bf16_f32 v85, v86, v87
	v_cvt_pk_bf16_f32 v86, v80, v81
	v_cvt_pk_bf16_f32 v87, v82, v83
	global_store_dwordx4 v[148:149], v[84:87], off offset:256
	v_lshl_add_u64 v[148:149], v[148:149], 0, s[98:99]
	v_fma_f32 v76, v76, s47, v162
	v_fma_f32 v77, v77, s47, v163
	v_fma_f32 v78, v78, s47, v164
	v_fma_f32 v79, v79, s47, v165
	v_fma_f32 v72, v72, s47, v166
	v_fma_f32 v73, v73, s47, v167
	v_fma_f32 v74, v74, s47, v168
	v_fma_f32 v75, v75, s47, v169
	v_fma_f32 v68, v68, s47, v170
	v_fma_f32 v69, v69, s47, v171
	v_fma_f32 v70, v70, s47, v172
	v_fma_f32 v71, v71, s47, v173
	v_fma_f32 v64, v64, s47, v174
	v_fma_f32 v65, v65, s47, v175
	v_fma_f32 v66, v66, s47, v176
	v_fma_f32 v67, v67, s47, v177
	v_exp_f32_e32 v76, v76
	v_exp_f32_e32 v77, v77
	v_exp_f32_e32 v78, v78
	v_exp_f32_e32 v79, v79
	v_exp_f32_e32 v72, v72
	v_exp_f32_e32 v73, v73
	v_exp_f32_e32 v74, v74
	v_exp_f32_e32 v75, v75
	v_exp_f32_e32 v68, v68
	v_exp_f32_e32 v69, v69
	v_exp_f32_e32 v70, v70
	v_exp_f32_e32 v71, v71
	v_exp_f32_e32 v64, v64
	v_exp_f32_e32 v65, v65
	v_exp_f32_e32 v66, v66
	v_exp_f32_e32 v67, v67
	v_add_f32_e32 v76, 1.0, v76
	v_add_f32_e32 v77, 1.0, v77
	v_add_f32_e32 v78, 1.0, v78
	v_add_f32_e32 v79, 1.0, v79
	v_add_f32_e32 v72, 1.0, v72
	v_add_f32_e32 v73, 1.0, v73
	v_add_f32_e32 v74, 1.0, v74
	v_add_f32_e32 v75, 1.0, v75
	v_add_f32_e32 v68, 1.0, v68
	v_add_f32_e32 v69, 1.0, v69
	v_add_f32_e32 v70, 1.0, v70
	v_add_f32_e32 v71, 1.0, v71
	v_add_f32_e32 v64, 1.0, v64
	v_add_f32_e32 v65, 1.0, v65
	v_add_f32_e32 v66, 1.0, v66
	v_add_f32_e32 v67, 1.0, v67
	v_rcp_f32_e32 v76, v76
	v_rcp_f32_e32 v77, v77
	v_rcp_f32_e32 v78, v78
	v_rcp_f32_e32 v79, v79
	v_rcp_f32_e32 v72, v72
	v_rcp_f32_e32 v73, v73
	v_rcp_f32_e32 v74, v74
	v_rcp_f32_e32 v75, v75
	v_rcp_f32_e32 v68, v68
	v_rcp_f32_e32 v69, v69
	v_rcp_f32_e32 v70, v70
	v_rcp_f32_e32 v71, v71
	v_rcp_f32_e32 v64, v64
	v_rcp_f32_e32 v65, v65
	v_rcp_f32_e32 v66, v66
	v_rcp_f32_e32 v67, v67
	v_cvt_pk_bf16_f32 v76, v76, v77
	v_cvt_pk_bf16_f32 v77, v78, v79
	v_cvt_pk_bf16_f32 v78, v72, v73
	v_cvt_pk_bf16_f32 v79, v74, v75
	global_store_dwordx4 v[148:149], v[76:79], off
	v_cvt_pk_bf16_f32 v68, v68, v69
	v_cvt_pk_bf16_f32 v69, v70, v71
	v_cvt_pk_bf16_f32 v70, v64, v65
	v_cvt_pk_bf16_f32 v71, v66, v67
	global_store_dwordx4 v[148:149], v[68:71], off offset:256
	v_lshl_add_u64 v[148:149], v[148:149], 0, s[100:101]
	v_fma_f32 v60, v60, s47, v162
	v_fma_f32 v61, v61, s47, v163
	v_fma_f32 v62, v62, s47, v164
	v_fma_f32 v63, v63, s47, v165
	v_fma_f32 v56, v56, s47, v166
	v_fma_f32 v57, v57, s47, v167
	v_fma_f32 v58, v58, s47, v168
	v_fma_f32 v59, v59, s47, v169
	v_fma_f32 v52, v52, s47, v170
	v_fma_f32 v53, v53, s47, v171
	v_fma_f32 v54, v54, s47, v172
	v_fma_f32 v55, v55, s47, v173
	v_fma_f32 v48, v48, s47, v174
	v_fma_f32 v49, v49, s47, v175
	v_fma_f32 v50, v50, s47, v176
	v_fma_f32 v51, v51, s47, v177
	v_exp_f32_e32 v60, v60
	v_exp_f32_e32 v61, v61
	v_exp_f32_e32 v62, v62
	v_exp_f32_e32 v63, v63
	v_exp_f32_e32 v56, v56
	v_exp_f32_e32 v57, v57
	v_exp_f32_e32 v58, v58
	v_exp_f32_e32 v59, v59
	v_exp_f32_e32 v52, v52
	v_exp_f32_e32 v53, v53
	v_exp_f32_e32 v54, v54
	v_exp_f32_e32 v55, v55
	v_exp_f32_e32 v48, v48
	v_exp_f32_e32 v49, v49
	v_exp_f32_e32 v50, v50
	v_exp_f32_e32 v51, v51
	v_add_f32_e32 v60, 1.0, v60
	v_add_f32_e32 v61, 1.0, v61
	v_add_f32_e32 v62, 1.0, v62
	v_add_f32_e32 v63, 1.0, v63
	v_add_f32_e32 v56, 1.0, v56
	v_add_f32_e32 v57, 1.0, v57
	v_add_f32_e32 v58, 1.0, v58
	v_add_f32_e32 v59, 1.0, v59
	v_add_f32_e32 v52, 1.0, v52
	v_add_f32_e32 v53, 1.0, v53
	v_add_f32_e32 v54, 1.0, v54
	v_add_f32_e32 v55, 1.0, v55
	v_add_f32_e32 v48, 1.0, v48
	v_add_f32_e32 v49, 1.0, v49
	v_add_f32_e32 v50, 1.0, v50
	v_add_f32_e32 v51, 1.0, v51
	v_rcp_f32_e32 v60, v60
	v_rcp_f32_e32 v61, v61
	v_rcp_f32_e32 v62, v62
	v_rcp_f32_e32 v63, v63
	v_rcp_f32_e32 v56, v56
	v_rcp_f32_e32 v57, v57
	v_rcp_f32_e32 v58, v58
	v_rcp_f32_e32 v59, v59
	v_rcp_f32_e32 v52, v52
	v_rcp_f32_e32 v53, v53
	v_rcp_f32_e32 v54, v54
	v_rcp_f32_e32 v55, v55
	v_rcp_f32_e32 v48, v48
	v_rcp_f32_e32 v49, v49
	v_rcp_f32_e32 v50, v50
	v_rcp_f32_e32 v51, v51
	v_cvt_pk_bf16_f32 v60, v60, v61
	v_cvt_pk_bf16_f32 v61, v62, v63
	v_cvt_pk_bf16_f32 v62, v56, v57
	v_cvt_pk_bf16_f32 v63, v58, v59
	global_store_dwordx4 v[148:149], v[60:63], off
	v_cvt_pk_bf16_f32 v52, v52, v53
	v_cvt_pk_bf16_f32 v53, v54, v55
	v_cvt_pk_bf16_f32 v54, v48, v49
	v_cvt_pk_bf16_f32 v55, v50, v51
	global_store_dwordx4 v[148:149], v[52:55], off offset:256
	v_lshl_add_u64 v[148:149], v[148:149], 0, s[98:99]
	v_fma_f32 v44, v44, s47, v162
	v_fma_f32 v45, v45, s47, v163
	v_fma_f32 v46, v46, s47, v164
	v_fma_f32 v47, v47, s47, v165
	v_fma_f32 v40, v40, s47, v166
	v_fma_f32 v41, v41, s47, v167
	v_fma_f32 v42, v42, s47, v168
	v_fma_f32 v43, v43, s47, v169
	v_fma_f32 v36, v36, s47, v170
	v_fma_f32 v37, v37, s47, v171
	v_fma_f32 v38, v38, s47, v172
	v_fma_f32 v39, v39, s47, v173
	v_fma_f32 v32, v32, s47, v174
	v_fma_f32 v33, v33, s47, v175
	v_fma_f32 v34, v34, s47, v176
	v_fma_f32 v35, v35, s47, v177
	v_exp_f32_e32 v44, v44
	v_exp_f32_e32 v45, v45
	v_exp_f32_e32 v46, v46
	v_exp_f32_e32 v47, v47
	v_exp_f32_e32 v40, v40
	v_exp_f32_e32 v41, v41
	v_exp_f32_e32 v42, v42
	v_exp_f32_e32 v43, v43
	v_exp_f32_e32 v36, v36
	v_exp_f32_e32 v37, v37
	v_exp_f32_e32 v38, v38
	v_exp_f32_e32 v39, v39
	v_exp_f32_e32 v32, v32
	v_exp_f32_e32 v33, v33
	v_exp_f32_e32 v34, v34
	v_exp_f32_e32 v35, v35
	v_add_f32_e32 v44, 1.0, v44
	v_add_f32_e32 v45, 1.0, v45
	v_add_f32_e32 v46, 1.0, v46
	v_add_f32_e32 v47, 1.0, v47
	v_add_f32_e32 v40, 1.0, v40
	v_add_f32_e32 v41, 1.0, v41
	v_add_f32_e32 v42, 1.0, v42
	v_add_f32_e32 v43, 1.0, v43
	v_add_f32_e32 v36, 1.0, v36
	v_add_f32_e32 v37, 1.0, v37
	v_add_f32_e32 v38, 1.0, v38
	v_add_f32_e32 v39, 1.0, v39
	v_add_f32_e32 v32, 1.0, v32
	v_add_f32_e32 v33, 1.0, v33
	v_add_f32_e32 v34, 1.0, v34
	v_add_f32_e32 v35, 1.0, v35
	v_rcp_f32_e32 v44, v44
	v_rcp_f32_e32 v45, v45
	v_rcp_f32_e32 v46, v46
	v_rcp_f32_e32 v47, v47
	v_rcp_f32_e32 v40, v40
	v_rcp_f32_e32 v41, v41
	v_rcp_f32_e32 v42, v42
	v_rcp_f32_e32 v43, v43
	v_rcp_f32_e32 v36, v36
	v_rcp_f32_e32 v37, v37
	v_rcp_f32_e32 v38, v38
	v_rcp_f32_e32 v39, v39
	v_rcp_f32_e32 v32, v32
	v_rcp_f32_e32 v33, v33
	v_rcp_f32_e32 v34, v34
	v_rcp_f32_e32 v35, v35
	v_cvt_pk_bf16_f32 v44, v44, v45
	v_cvt_pk_bf16_f32 v45, v46, v47
	v_cvt_pk_bf16_f32 v46, v40, v41
	v_cvt_pk_bf16_f32 v47, v42, v43
	global_store_dwordx4 v[148:149], v[44:47], off
	v_cvt_pk_bf16_f32 v36, v36, v37
	v_cvt_pk_bf16_f32 v37, v38, v39
	v_cvt_pk_bf16_f32 v38, v32, v33
	v_cvt_pk_bf16_f32 v39, v34, v35
	global_store_dwordx4 v[148:149], v[36:39], off offset:256
	v_lshl_add_u64 v[148:149], v[148:149], 0, s[98:99]
	v_fma_f32 v28, v28, s47, v162
	v_fma_f32 v29, v29, s47, v163
	v_fma_f32 v30, v30, s47, v164
	v_fma_f32 v31, v31, s47, v165
	v_fma_f32 v24, v24, s47, v166
	v_fma_f32 v25, v25, s47, v167
	v_fma_f32 v26, v26, s47, v168
	v_fma_f32 v27, v27, s47, v169
	v_fma_f32 v20, v20, s47, v170
	v_fma_f32 v21, v21, s47, v171
	v_fma_f32 v22, v22, s47, v172
	v_fma_f32 v23, v23, s47, v173
	v_fma_f32 v16, v16, s47, v174
	v_fma_f32 v17, v17, s47, v175
	v_fma_f32 v18, v18, s47, v176
	v_fma_f32 v19, v19, s47, v177
	v_exp_f32_e32 v28, v28
	v_exp_f32_e32 v29, v29
	v_exp_f32_e32 v30, v30
	v_exp_f32_e32 v31, v31
	v_exp_f32_e32 v24, v24
	v_exp_f32_e32 v25, v25
	v_exp_f32_e32 v26, v26
	v_exp_f32_e32 v27, v27
	v_exp_f32_e32 v20, v20
	v_exp_f32_e32 v21, v21
	v_exp_f32_e32 v22, v22
	v_exp_f32_e32 v23, v23
	v_exp_f32_e32 v16, v16
	v_exp_f32_e32 v17, v17
	v_exp_f32_e32 v18, v18
	v_exp_f32_e32 v19, v19
	v_add_f32_e32 v28, 1.0, v28
	v_add_f32_e32 v29, 1.0, v29
	v_add_f32_e32 v30, 1.0, v30
	v_add_f32_e32 v31, 1.0, v31
	v_add_f32_e32 v24, 1.0, v24
	v_add_f32_e32 v25, 1.0, v25
	v_add_f32_e32 v26, 1.0, v26
	v_add_f32_e32 v27, 1.0, v27
	v_add_f32_e32 v20, 1.0, v20
	v_add_f32_e32 v21, 1.0, v21
	v_add_f32_e32 v22, 1.0, v22
	v_add_f32_e32 v23, 1.0, v23
	v_add_f32_e32 v16, 1.0, v16
	v_add_f32_e32 v17, 1.0, v17
	v_add_f32_e32 v18, 1.0, v18
	v_add_f32_e32 v19, 1.0, v19
	v_rcp_f32_e32 v28, v28
	v_rcp_f32_e32 v29, v29
	v_rcp_f32_e32 v30, v30
	v_rcp_f32_e32 v31, v31
	v_rcp_f32_e32 v24, v24
	v_rcp_f32_e32 v25, v25
	v_rcp_f32_e32 v26, v26
	v_rcp_f32_e32 v27, v27
	v_rcp_f32_e32 v20, v20
	v_rcp_f32_e32 v21, v21
	v_rcp_f32_e32 v22, v22
	v_rcp_f32_e32 v23, v23
	v_rcp_f32_e32 v16, v16
	v_rcp_f32_e32 v17, v17
	v_rcp_f32_e32 v18, v18
	v_rcp_f32_e32 v19, v19
	v_cvt_pk_bf16_f32 v28, v28, v29
	v_cvt_pk_bf16_f32 v29, v30, v31
	v_cvt_pk_bf16_f32 v30, v24, v25
	v_cvt_pk_bf16_f32 v31, v26, v27
	global_store_dwordx4 v[148:149], v[28:31], off
	v_cvt_pk_bf16_f32 v20, v20, v21
	v_cvt_pk_bf16_f32 v21, v22, v23
	v_cvt_pk_bf16_f32 v22, v16, v17
	v_cvt_pk_bf16_f32 v23, v18, v19
	global_store_dwordx4 v[148:149], v[20:23], off offset:256
	v_lshl_add_u64 v[148:149], v[148:149], 0, s[98:99]
	v_fma_f32 v12, v12, s47, v162
	v_fma_f32 v13, v13, s47, v163
	v_fma_f32 v14, v14, s47, v164
	v_fma_f32 v15, v15, s47, v165
	v_fma_f32 v8, v8, s47, v166
	v_fma_f32 v9, v9, s47, v167
	v_fma_f32 v10, v10, s47, v168
	v_fma_f32 v11, v11, s47, v169
	v_fma_f32 v4, v4, s47, v170
	v_fma_f32 v5, v5, s47, v171
	v_fma_f32 v6, v6, s47, v172
	v_fma_f32 v7, v7, s47, v173
	v_fma_f32 v0, v0, s47, v174
	v_fma_f32 v1, v1, s47, v175
	v_fma_f32 v2, v2, s47, v176
	v_fma_f32 v3, v3, s47, v177
	v_exp_f32_e32 v12, v12
	v_exp_f32_e32 v13, v13
	v_exp_f32_e32 v14, v14
	v_exp_f32_e32 v15, v15
	v_exp_f32_e32 v8, v8
	v_exp_f32_e32 v9, v9
	v_exp_f32_e32 v10, v10
	v_exp_f32_e32 v11, v11
	v_exp_f32_e32 v4, v4
	v_exp_f32_e32 v5, v5
	v_exp_f32_e32 v6, v6
	v_exp_f32_e32 v7, v7
	v_exp_f32_e32 v0, v0
	v_exp_f32_e32 v1, v1
	v_exp_f32_e32 v2, v2
	v_exp_f32_e32 v3, v3
	v_add_f32_e32 v12, 1.0, v12
	v_add_f32_e32 v13, 1.0, v13
	v_add_f32_e32 v14, 1.0, v14
	v_add_f32_e32 v15, 1.0, v15
	v_add_f32_e32 v8, 1.0, v8
	v_add_f32_e32 v9, 1.0, v9
	v_add_f32_e32 v10, 1.0, v10
	v_add_f32_e32 v11, 1.0, v11
	v_add_f32_e32 v4, 1.0, v4
	v_add_f32_e32 v5, 1.0, v5
	v_add_f32_e32 v6, 1.0, v6
	v_add_f32_e32 v7, 1.0, v7
	v_add_f32_e32 v0, 1.0, v0
	v_add_f32_e32 v1, 1.0, v1
	v_add_f32_e32 v2, 1.0, v2
	v_add_f32_e32 v3, 1.0, v3
	v_rcp_f32_e32 v12, v12
	v_rcp_f32_e32 v13, v13
	v_rcp_f32_e32 v14, v14
	v_rcp_f32_e32 v15, v15
	v_rcp_f32_e32 v8, v8
	v_rcp_f32_e32 v9, v9
	v_rcp_f32_e32 v10, v10
	v_rcp_f32_e32 v11, v11
	v_rcp_f32_e32 v4, v4
	v_rcp_f32_e32 v5, v5
	v_rcp_f32_e32 v6, v6
	v_rcp_f32_e32 v7, v7
	v_rcp_f32_e32 v0, v0
	v_rcp_f32_e32 v1, v1
	v_rcp_f32_e32 v2, v2
	v_rcp_f32_e32 v3, v3
	v_cvt_pk_bf16_f32 v12, v12, v13
	v_cvt_pk_bf16_f32 v13, v14, v15
	v_cvt_pk_bf16_f32 v14, v8, v9
	v_cvt_pk_bf16_f32 v15, v10, v11
	global_store_dwordx4 v[148:149], v[12:15], off
	v_cvt_pk_bf16_f32 v4, v4, v5
	v_cvt_pk_bf16_f32 v5, v6, v7
	v_cvt_pk_bf16_f32 v6, v0, v1
	v_cvt_pk_bf16_f32 v7, v2, v3
	global_store_dwordx4 v[148:149], v[4:7], off offset:256
	s_branch .LBB0_396
